# GEMM prologues: K-tile-1 DMA loads issued before the first wait (one exposed latency less per GEMM phase)
# speedup vs baseline: 1.0017x; 1.0004x over previous
; #define STAGE(bufoff, GB) do { const char* g_ = (GB); \
;         _Pragma("unroll") for (int i_ = 0; i_ < 2; ++i_) __builtin_amdgcn_global_load_lds((const unsigned*)(g_ + voff[i_]), (LAS3 unsigned*)(L + (bufoff) + stoff + i_ * 8192), 16, 0, 0); } while (0)
; #define WAIT_V(n) asm volatile("s_waitcnt vmcnt(" #n ")" ::: "memory")
; #define BAR __builtin_amdgcn_s_barrier()
; template <int EPI>
; DI void gemm_phase(const bf16_t* __restrict__ A, const bf16_t* __restrict__ Bt, const int K, const int N, const Params& p, const int layer_j, char* lds) {
;     ...
;         asm volatile("s_waitcnt vmcnt(0) lgkmcnt(0)" ::: "memory");
;         __syncthreads();
;         STAGE(SB(0, 0), cB); STAGE(SB(0, 1), cB + hstep); STAGE(SA(0, 0), cA); STAGE(SA(0, 1), cA + hstep);
;         if (wr == 1) BAR;
;         WAIT_V(2); BAR;
;         STAGE(SB(1, 0), cB + kstep); STAGE(SA(1, 0), cA + kstep); STAGE(SB(1, 1), cB + hstep + kstep);
;         WAIT_V(6); BAR;
;     }
.LBB0_37:
	v_add_u32_e32 v146, 0x18000, v136
	v_lshl_add_u64 v[2:3], s[12:13], 0, v[32:33]
	v_mov_b32_e32 v1, v33
	v_readfirstlane_b32 s6, v146
	v_add_u32_e32 v147, 0x1a000, v136
	v_lshl_add_u64 v[4:5], s[12:13], 0, v[0:1]
	v_lshl_add_u64 v[2:3], v[2:3], 0, s[94:95]
	s_mov_b32 m0, s6
	v_readfirstlane_b32 s6, v147
	v_add_u32_e32 v148, 0x8000, v136
	v_lshl_add_u64 v[6:7], s[8:9], 0, v[32:33]
	global_load_lds_dwordx4 v[2:3], off
	v_lshl_add_u64 v[2:3], v[4:5], 0, s[94:95]
	s_mov_b32 m0, s6
	v_readfirstlane_b32 s6, v148
	v_add_u32_e32 v149, 0xa000, v136
	v_lshl_add_u64 v[8:9], s[8:9], 0, v[0:1]
	global_load_lds_dwordx4 v[2:3], off
	v_lshl_add_u64 v[2:3], v[6:7], 0, s[94:95]
	s_mov_b32 m0, s6
	v_readfirstlane_b32 s6, v149
	s_add_u32 s8, s12, 0x40080
	v_add_u32_e32 v150, 0x1c000, v136
	global_load_lds_dwordx4 v[2:3], off
	v_lshl_add_u64 v[2:3], v[8:9], 0, s[94:95]
	s_mov_b32 m0, s6
	s_addc_u32 s9, s13, 0
	v_readfirstlane_b32 s6, v150
	v_add_u32_e32 v151, 0x1e000, v136
	global_load_lds_dwordx4 v[2:3], off
	v_lshl_add_u64 v[2:3], s[8:9], 0, v[32:33]
	s_mov_b32 m0, s6
	v_readfirstlane_b32 s6, v151
	global_load_lds_dwordx4 v[2:3], off
	v_lshl_add_u64 v[0:1], s[8:9], 0, v[0:1]
	s_mov_b32 m0, s6
	s_add_u32 s8, s68, 0x8681000
	global_load_lds_dwordx4 v[0:1], off
	v_readlane_b32 vcc_lo, v254, 10
	v_readlane_b32 vcc_hi, v254, 11
	s_nop 3
	s_mov_b64 vcc, vcc
	s_cbranch_vccz .Lpro_skip_0
	s_barrier
.Lpro_skip_0:
	s_waitcnt vmcnt(8)
	s_barrier
	s_addc_u32 s9, s69, 0
	s_add_u32 s6, s68, s17
	s_addc_u32 s7, s69, s16
	s_add_u32 s27, s6, 0x2481100
	s_waitcnt vmcnt(6)
	s_addc_u32 s66, s7, 0
	s_add_u32 s67, s68, 0x66c1080
	s_addc_u32 s86, s69, 0
	s_mov_b32 s87, 0
	s_barrier
	s_branch .LBB0_40

; #define STAGE(bufoff, GB) do { const char* g_ = (GB); \
;         _Pragma("unroll") for (int i_ = 0; i_ < 2; ++i_) __builtin_amdgcn_global_load_lds((const unsigned*)(g_ + voff[i_]), (LAS3 unsigned*)(L + (bufoff) + stoff + i_ * 8192), 16, 0, 0); } while (0)
; #define WAIT_V(n) asm volatile("s_waitcnt vmcnt(" #n ")" ::: "memory")
; #define BAR __builtin_amdgcn_s_barrier()
; template <int EPI>
; DI void gemm_phase(const bf16_t* __restrict__ A, const bf16_t* __restrict__ Bt, const int K, const int N, const Params& p, const int layer_j, char* lds) {
;     ...
;         asm volatile("s_waitcnt vmcnt(0) lgkmcnt(0)" ::: "memory");
;         __syncthreads();
;         STAGE(SB(0, 0), cB); STAGE(SB(0, 1), cB + hstep); STAGE(SA(0, 0), cA); STAGE(SA(0, 1), cA + hstep);
;         if (wr == 1) BAR;
;         WAIT_V(2); BAR;
;         STAGE(SB(1, 0), cB + kstep); STAGE(SA(1, 0), cA + kstep); STAGE(SB(1, 1), cB + hstep + kstep);
;         WAIT_V(6); BAR;
;     }
.LBB0_96:
	v_mov_b32_e32 v1, v33
	v_add_u32_e32 v146, 0x18000, v136
	v_lshl_add_u64 v[2:3], s[8:9], 0, v[32:33]
	v_lshl_add_u64 v[4:5], s[8:9], 0, v[0:1]
	v_readfirstlane_b32 s8, v146
	v_add_u32_e32 v147, 0x1a000, v136
	v_lshl_add_u64 v[2:3], v[2:3], 0, s[94:95]
	s_mov_b32 m0, s8
	v_readfirstlane_b32 s8, v147
	v_add_u32_e32 v148, 0x8000, v136
	v_lshl_add_u64 v[10:11], s[18:19], 0, v[32:33]
	global_load_lds_dwordx4 v[2:3], off
	v_lshl_add_u64 v[2:3], v[4:5], 0, s[94:95]
	s_mov_b32 m0, s8
	v_readfirstlane_b32 s8, v148
	v_add_u32_e32 v149, 0xa000, v136
	v_lshl_add_u64 v[8:9], s[10:11], 0, v[0:1]
	v_lshl_add_u64 v[0:1], s[18:19], 0, v[0:1]
	global_load_lds_dwordx4 v[2:3], off
	v_lshl_add_u64 v[2:3], v[10:11], 0, s[94:95]
	s_mov_b32 m0, s8
	v_readfirstlane_b32 s8, v149
	v_add_u32_e32 v150, 0x1c000, v136
	v_lshl_add_u64 v[6:7], s[10:11], 0, v[32:33]
	global_load_lds_dwordx4 v[2:3], off
	v_lshl_add_u64 v[0:1], v[0:1], 0, s[94:95]
	s_mov_b32 m0, s8
	v_readfirstlane_b32 s8, v150
	v_add_u32_e32 v151, 0x1e000, v136
	global_load_lds_dwordx4 v[0:1], off
	v_lshl_add_u64 v[0:1], v[6:7], 0, s[94:95]
	s_mov_b32 m0, s8
	v_readfirstlane_b32 s8, v151
	global_load_lds_dwordx4 v[0:1], off
	v_lshl_add_u64 v[0:1], v[8:9], 0, s[94:95]
	s_mov_b32 m0, s8
	s_lshr_b32 s24, s20, 6
	global_load_lds_dwordx4 v[0:1], off
	v_readlane_b32 vcc_lo, v254, 10
	v_readlane_b32 vcc_hi, v254, 11
	s_nop 3
	s_mov_b64 vcc, vcc
	s_cbranch_vccz .Lpro_skip_1
	s_barrier
.Lpro_skip_1:
	s_waitcnt vmcnt(8)
	s_barrier
	s_add_i32 s25, s24, -2
	s_add_u32 s8, s68, 0x10681000
	s_waitcnt vmcnt(6)
	s_addc_u32 s9, s69, 0
	s_add_u32 s26, s6, 0x100
	s_addc_u32 s27, s7, 0
	s_mov_b32 s28, 0
	s_mov_b32 s29, s34
	s_mov_b32 s30, s31
	s_barrier
	s_branch .LBB0_99

; #define STAGE(bufoff, GB) do { const char* g_ = (GB); \
;         _Pragma("unroll") for (int i_ = 0; i_ < 2; ++i_) __builtin_amdgcn_global_load_lds((const unsigned*)(g_ + voff[i_]), (LAS3 unsigned*)(L + (bufoff) + stoff + i_ * 8192), 16, 0, 0); } while (0)
; #define WAIT_V(n) asm volatile("s_waitcnt vmcnt(" #n ")" ::: "memory")
; #define BAR __builtin_amdgcn_s_barrier()
; template <int EPI>
; DI void gemm_phase(const bf16_t* __restrict__ A, const bf16_t* __restrict__ Bt, const int K, const int N, const Params& p, const int layer_j, char* lds) {
;     ...
;         asm volatile("s_waitcnt vmcnt(0) lgkmcnt(0)" ::: "memory");
;         __syncthreads();
;         STAGE(SB(0, 0), cB); STAGE(SB(0, 1), cB + hstep); STAGE(SA(0, 0), cA); STAGE(SA(0, 1), cA + hstep);
;         if (wr == 1) BAR;
;         WAIT_V(2); BAR;
;         STAGE(SB(1, 0), cB + kstep); STAGE(SA(1, 0), cA + kstep); STAGE(SB(1, 1), cB + hstep + kstep);
;         WAIT_V(6); BAR;
;     }
.LBB0_328:
	v_add_u32_e32 v206, 0x18000, v184
	v_lshl_add_u64 v[2:3], s[12:13], 0, v[32:33]
	v_mov_b32_e32 v1, v33
	v_readfirstlane_b32 s5, v206
	v_add_u32_e32 v207, 0x1a000, v184
	v_lshl_add_u64 v[4:5], s[12:13], 0, v[0:1]
	v_lshl_add_u64 v[2:3], v[2:3], 0, s[94:95]
	s_mov_b32 m0, s5
	v_readfirstlane_b32 s5, v207
	v_add_u32_e32 v208, 0x8000, v184
	v_lshl_add_u64 v[6:7], s[10:11], 0, v[32:33]
	global_load_lds_dwordx4 v[2:3], off
	v_lshl_add_u64 v[2:3], v[4:5], 0, s[94:95]
	s_mov_b32 m0, s5
	v_readfirstlane_b32 s5, v208
	v_add_u32_e32 v209, 0xa000, v184
	v_lshl_add_u64 v[8:9], s[10:11], 0, v[0:1]
	global_load_lds_dwordx4 v[2:3], off
	v_lshl_add_u64 v[2:3], v[6:7], 0, s[94:95]
	s_mov_b32 m0, s5
	v_readfirstlane_b32 s5, v209
	s_add_u32 s10, s12, 0x40080
	v_add_u32_e32 v210, 0x1c000, v184
	global_load_lds_dwordx4 v[2:3], off
	v_lshl_add_u64 v[2:3], v[8:9], 0, s[94:95]
	s_mov_b32 m0, s5
	s_addc_u32 s11, s13, 0
	v_readfirstlane_b32 s5, v210
	v_add_u32_e32 v211, 0x1e000, v184
	global_load_lds_dwordx4 v[2:3], off
	v_lshl_add_u64 v[2:3], s[10:11], 0, v[32:33]
	s_mov_b32 m0, s5
	v_readfirstlane_b32 s5, v211
	global_load_lds_dwordx4 v[2:3], off
	v_lshl_add_u64 v[0:1], s[10:11], 0, v[0:1]
	s_mov_b32 m0, s5
	s_add_u32 s10, s68, 0x8681000
	global_load_lds_dwordx4 v[0:1], off
	v_readlane_b32 vcc_lo, v254, 10
	v_readlane_b32 vcc_hi, v254, 11
	s_nop 3
	s_mov_b64 vcc, vcc
	s_cbranch_vccz .Lpro_skip_2
	s_barrier
.Lpro_skip_2:
	s_waitcnt vmcnt(8)
	s_barrier
	s_addc_u32 s11, s69, 0
	s_add_u32 s12, s68, 0x10681000
	s_addc_u32 s13, s69, 0
	s_cmp_eq_u32 s14, 1
	s_cselect_b64 s[14:15], -1, 0
	s_add_u32 s6, s68, 0xe681000
	s_addc_u32 s7, s69, 0
	s_add_u32 s5, s68, s18
	s_addc_u32 s9, s69, s19
	s_add_u32 s38, s5, 0x1081100
	s_waitcnt vmcnt(6)
	s_addc_u32 s39, s9, 0
	v_writelane_b32 v255, s6, 8
	s_add_u32 s64, s68, 0x66c1080
	s_addc_u32 s65, s69, 0
	v_writelane_b32 v255, s7, 9
	s_mov_b32 s66, 0
	s_barrier
	s_branch .LBB0_331

; #define STAGE(bufoff, GB) do { const char* g_ = (GB); \
;         _Pragma("unroll") for (int i_ = 0; i_ < 2; ++i_) __builtin_amdgcn_global_load_lds((const unsigned*)(g_ + voff[i_]), (LAS3 unsigned*)(L + (bufoff) + stoff + i_ * 8192), 16, 0, 0); } while (0)
; #define WAIT_V(n) asm volatile("s_waitcnt vmcnt(" #n ")" ::: "memory")
; #define BAR __builtin_amdgcn_s_barrier()
; template <int EPI>
; DI void gemm_phase(const bf16_t* __restrict__ A, const bf16_t* __restrict__ Bt, const int K, const int N, const Params& p, const int layer_j, char* lds) {
;     ...
;         asm volatile("s_waitcnt vmcnt(0) lgkmcnt(0)" ::: "memory");
;         __syncthreads();
;         STAGE(SB(0, 0), cB); STAGE(SB(0, 1), cB + hstep); STAGE(SA(0, 0), cA); STAGE(SA(0, 1), cA + hstep);
;         if (wr == 1) BAR;
;         WAIT_V(2); BAR;
;         STAGE(SB(1, 0), cB + kstep); STAGE(SA(1, 0), cA + kstep); STAGE(SB(1, 1), cB + hstep + kstep);
;         WAIT_V(6); BAR;
;     }
.LBB0_368:
	v_mov_b32_e32 v1, v33
	v_add_u32_e32 v148, 0x18000, v138
	v_lshl_add_u64 v[2:3], s[8:9], 0, v[32:33]
	v_lshl_add_u64 v[6:7], s[6:7], 0, v[32:33]
	v_lshl_add_u64 v[8:9], s[6:7], 0, v[0:1]
	v_readfirstlane_b32 s6, v148
	v_add_u32_e32 v149, 0x1a000, v138
	v_lshl_add_u64 v[4:5], s[8:9], 0, v[0:1]
	v_lshl_add_u64 v[2:3], v[2:3], 0, s[94:95]
	s_mov_b32 m0, s6
	v_readfirstlane_b32 s6, v149
	v_add_u32_e32 v150, 0x8000, v138
	global_load_lds_dwordx4 v[2:3], off
	v_lshl_add_u64 v[2:3], v[4:5], 0, s[94:95]
	s_mov_b32 m0, s6
	v_readfirstlane_b32 s6, v150
	v_add_u32_e32 v151, 0xa000, v138
	global_load_lds_dwordx4 v[2:3], off
	v_lshl_add_u64 v[2:3], v[6:7], 0, s[94:95]
	s_mov_b32 m0, s6
	v_readfirstlane_b32 s6, v151
	global_load_lds_dwordx4 v[2:3], off
	s_mov_b32 m0, s6
	s_add_u32 s6, s8, 0x40080
	v_add_u32_e32 v152, 0x1c000, v138
	v_lshl_add_u64 v[2:3], v[8:9], 0, s[94:95]
	s_addc_u32 s7, s9, 0
	v_readfirstlane_b32 s8, v152
	v_add_u32_e32 v153, 0x1e000, v138
	global_load_lds_dwordx4 v[2:3], off
	v_lshl_add_u64 v[2:3], s[6:7], 0, v[32:33]
	s_mov_b32 m0, s8
	v_lshl_add_u64 v[0:1], s[6:7], 0, v[0:1]
	v_readfirstlane_b32 s6, v153
	global_load_lds_dwordx4 v[2:3], off
	s_mov_b32 m0, s6
	s_add_u32 s6, s68, 0xe681000
	global_load_lds_dwordx4 v[0:1], off
	v_readlane_b32 vcc_lo, v254, 10
	v_readlane_b32 vcc_hi, v254, 11
	s_nop 3
	s_mov_b64 vcc, vcc
	s_cbranch_vccz .Lpro_skip_3
	s_barrier
.Lpro_skip_3:
	s_waitcnt vmcnt(8)
	s_barrier
	s_addc_u32 s7, s69, 0
	s_add_u32 s8, s68, 0x8681000
	s_addc_u32 s9, s69, 0
	s_add_u32 s10, s68, 0x1000
	s_addc_u32 s11, s69, 0
	s_add_u32 s13, s68, s13
	s_addc_u32 s12, s69, s12
	s_add_u32 s25, s13, 0x81100
	s_waitcnt vmcnt(6)
	s_addc_u32 s36, s12, 0
	s_add_u32 s37, s68, 0x66c1080
	s_addc_u32 s38, s69, 0
	s_mov_b32 s39, 0
	s_barrier
	s_branch .LBB0_371
